# HGRN2 chunk unit: decay-vector copy into LDS with four loads in flight instead of a four-trip load-wait-write loop
# baseline (speedup 1.0000x reference)
; __device__ __forceinline__ void hg_c2_unit(const Args& a, const float* Gp, LAS unsigned char* lds, int unit, int tid) {
;     ...
;         for (int i = tid; i < 16 * 128; i += NT) DGL[i] = ((const float*)(ws + WS_DEC))[bh * 16 * 128 + i];
;         const int q = g >> 2, gi = g & 3;
;         const float* tbase = Gp + (size_t)(256 + bh * 4) * 16384 + (size_t)(wave * 8) * 256 + lane * 4;
;         f32x4 ta[8], tb[8], tc[8], pg[8];
; #pragma unroll
;         for (int kt = 0; kt < 8; ++kt) { const f32x4 z = {0.f, 0.f, 0.f, 0.f};
;             ta[kt] = q >= 1 ? *(const f32x4*)(tbase + (size_t)(q - 1) * 16384 + kt * 256) : z;
;             tb[kt] = q >= 2 ? *(const f32x4*)(tbase + (size_t)(q - 2) * 16384 + kt * 256) : z;
;             tc[kt] = q >= 3 ? *(const f32x4*)(tbase + (size_t)(q - 3) * 16384 + kt * 256) : z;
;             pg[kt] = gi >= 1 ? *(const f32x4*)(Gp + (size_t)unit * 16384 + (size_t)(wave * 8) * 256 + lane * 4 + kt * 256) : z; }
.LBB0_779:
	s_and_b32 s36, s59, 0xfffff800
	s_mov_b64 s[34:35], 0
	v_add_u32_e32 v6, s36, v209
	v_lshlrev_b32_e32 v6, 2, v6
	v_add_u32_e32 v7, 0x1000, v6
	global_load_dword v3, v6, s[64:65]
	global_load_dword v5, v6, s[64:65] offset:2048
	global_load_dword v2, v7, s[64:65]
	global_load_dword v1, v7, s[64:65] offset:2048
	s_waitcnt vmcnt(0)
	ds_write_b32 v198, v3
	ds_write_b32 v198, v5 offset:2048
	ds_write_b32 v198, v2 offset:4096
	ds_write_b32 v198, v1 offset:6144
	s_or_b64 exec, exec, s[34:35]
	s_ashr_i32 s90, s60, 4
	s_lshl_b32 s34, s90, 2
	s_ashr_i32 s35, s34, 31
	s_and_b32 s91, s60, 15
	s_bfe_u32 s38, s60, 0x20002
	s_lshl_b64 s[34:35], s[34:35], 16
	s_cmp_gt_u32 s91, 3
	v_lshl_add_u64 v[2:3], v[138:139], 0, s[34:35]
	s_cselect_b64 s[34:35], -1, 0
	s_add_i32 s66, s38, -1
	v_lshl_add_u64 v[6:7], v[2:3], 0, s[74:75]
	s_lshl_b64 s[36:37], s[66:67], 16
	v_lshl_add_u64 v[64:65], v[6:7], 0, s[36:37]
	s_and_b64 vcc, exec, s[34:35]
	s_cbranch_vccz .LBB0_783
	global_load_dwordx4 v[8:11], v[64:65], off
	s_branch .LBB0_784
